# FoX: softmax row sum accumulated by f32 VALU adds of the exponentials instead of a ones-row MFMA per k-step (18 instead of 22 MFMAs per tile)
# speedup vs baseline: 1.0046x; 1.0008x over previous
; __device__ __forceinline__ void sb_unit(int b, int hh, int qb, const bf16_t* Q, const bf16_t* __restrict__ K, const bf16_t* __restrict__ V, bf16_t* O, float* SS, LAS3 unsigned char* shm) {
;     ...
;     const int tid = threadIdx.x, lane = tid & 63, r32 = lane & 31, hi = lane >> 5; const int wid = __builtin_amdgcn_readfirstlane(tid >> 6);
;     const long rowbase = (long)b * SEQ; const int q0 = qb * 256, qw0 = q0 + wid * 32;
;     const bf16_t* Qw = Q + (rowbase + qw0) * DM + hh * 64;
;     const bf16_t* Kh = K + rowbase * DM + hh * 64; const bf16_t* Vh = V + rowbase * DM + hh * 64;
;     const unsigned lds0 = (unsigned)(uintptr_t)shm;
;     const bf16_t* ksrc = Kh + (long)lane * DM + wid * 8;
;     const bf16_t* vsrc = Vh + (long)(16 * (wid & 3) + (lane >> 2)) * DM + (wid >> 2) * 32 + (lane & 3) * 8;
;     const int T_hi = 4 * qb + 3, T_lo = (4 * qb - 3 > 0) ? 4 * qb - 3 : 0;
;     for (int t = T_hi; t >= T_lo; --t) { glds16(ksrc + (long)t * KVB * DM, (unsigned)__builtin_amdgcn_readfirstlane(lds0 + (t - T_lo) * SLOTB + wid * 1024));
;                                          glds16(vsrc + (long)t * KVB * DM, (unsigned)__builtin_amdgcn_readfirstlane(lds0 + WV + (t - T_lo) * SLOTB + wid * 1024)); }
; __global__ void __launch_bounds__(NWAVES * 64, 2) fwd_megakernel(Args args) {
;     ...
;             const unsigned idx = qw[0];
;             if (idx >= 2048u) break;
;             if (idx < 1024u) { const int qb = 31 - (int)(idx >> 5), bh = (int)(idx & 31);
;                 att::fox_unit(bh >> 3, bh & 7, qb, QB, KB, VB, OB, F2, FS3, CTL + 64, SS, lds); }
;             else { const int u = (int)idx - 1024, qb = 31 - (u >> 5), bh = u & 31;
;                 att::sb_unit(bh >> 3, 8 + (bh & 7), qb, QB, KB, VB, OB, SS, lds); }
.LBB0_363:
	s_or_b64 exec, exec, s[0:1]
	s_waitcnt lgkmcnt(0)
	s_barrier
	ds_read_b32 v2, v173
	s_movk_i32 s0, 0x7ff
	s_waitcnt lgkmcnt(0)
	v_cmp_lt_u32_e32 vcc, s0, v2
	v_readfirstlane_b32 s77, v2
	s_mov_b64 s[0:1], -1
	s_cbranch_vccnz .LBB0_358
	s_cmpk_gt_u32 s77, 0x3ff
	s_cbranch_scc0 .LBB0_408
	s_add_i32 s0, s77, 0xfffffc00
	s_lshr_b32 s2, s0, 5
	s_bfe_u32 s1, s77, 0x20003
	s_and_b32 s84, s77, 7
	v_readfirstlane_b32 s3, v178
	s_sub_i32 s0, 31, s2
	s_or_b32 s6, s84, 8
	s_lshr_b32 s5, s3, 6
	s_lshl_b32 s7, s1, 24
	s_add_u32 s10, s88, s7
	s_addc_u32 s11, s95, 0
	s_lshl_b32 s12, s6, 7
	s_add_u32 s10, s10, s12
	s_addc_u32 s11, s11, 0
	s_add_u32 s7, s96, s7
	s_addc_u32 s13, s97, 0
	s_add_u32 s12, s7, s12
	v_mov_b32_e32 v153, v3
	s_addc_u32 s13, s13, 0
	v_lshl_add_u64 v[4:5], s[10:11], 0, v[152:153]
	s_lshl_b32 s80, s5, 4
	s_lshr_b32 s3, s3, 2
	v_lshl_add_u64 v[98:99], v[4:5], 0, s[80:81]
	v_and_b32_e32 v246, 63, v178
	v_lshrrev_b32_e32 v247, 4, v246
	s_and_b32 s101, s5, 1
	s_lshl_b32 s101, s101, 2
	v_add_u32_e32 v247, s101, v247
	v_and_b32_e32 v239, 7, v246
	v_xor_b32_e32 v247, v239, v247
	v_lshlrev_b32_e32 v247, 4, v247
	v_lshrrev_b32_e32 v239, 3, v246
	v_lshl_add_u32 v247, v239, 11, v247
	s_lshl_b32 s101, s5, 14
	v_add_u32_e32 v244, s101, v247
	v_mov_b32_e32 v245, 0
	v_lshl_add_u64 v[244:245], s[10:11], 0, v[244:245]
	v_and_b32_e32 v247, 31, v246
	v_lshrrev_b32_e32 v246, 5, v246
	v_bfe_u32 v236, v247, 1, 3
	v_lshlrev_b32_e32 v238, 4, v247
	v_lshl_add_u32 v238, v246, 10, v238
	v_lshlrev_b32_e32 v237, 7, v247
	v_sub_u32_e32 v237, v237, v238
	v_add_u32_e32 v239, 0, v246
	v_xor_b32_e32 v239, v239, v236
	v_lshl_add_u32 v240, v239, 4, v237
	v_add_u32_e32 v239, 2, v246
	v_xor_b32_e32 v239, v239, v236
	v_lshl_add_u32 v241, v239, 4, v237
	v_add_u32_e32 v239, 4, v246
	v_xor_b32_e32 v239, v239, v236
	v_lshl_add_u32 v242, v239, 4, v237
	v_add_u32_e32 v239, 6, v246
	v_xor_b32_e32 v239, v239, v236
	v_lshl_add_u32 v243, v239, 4, v237
	v_and_or_b32 v2, s3, 48, v135
	s_and_b32 s80, s3, 0x3fffffc0
	s_lshl_b32 s3, s0, 2
	v_lshlrev_b32_e32 v2, 10, v2
	s_or_b32 s7, s3, 3
	s_add_i32 s3, s3, -3
	v_lshl_add_u64 v[4:5], v[2:3], 1, s[12:13]
	s_cmp_lg_u32 s2, 31
	v_lshl_add_u64 v[4:5], v[4:5], 0, s[80:81]
	v_mov_b32_e32 v155, v3
	s_cselect_b32 s3, s3, 0
	s_cmp_lt_i32 s7, s3
	v_lshl_add_u64 v[100:101], v[4:5], 0, v[154:155]
	s_cbranch_scc1 .LBB0_368
	s_lshl_b32 s7, s5, 10
	s_lshl_b32 s10, s2, 2
	s_sub_i32 s80, 0x80, s10
	s_add_i32 s7, s7, 0
	s_lshl_b32 s10, s3, 13
	s_sub_i32 s7, s7, s10
	s_lshl_b32 s10, s2, 15
	s_sub_i32 s7, s7, s10
	s_add_i32 s7, s7, 0x10c000

; __device__ __forceinline__ void fox_unit(int b, int hh, int qb, const bf16_t* Q, const bf16_t* __restrict__ K, const bf16_t* __restrict__ V, bf16_t* O, ...
;     ...
;     const int tid = threadIdx.x, lane = tid & 63, r32 = lane & 31, hi = lane >> 5; const int wid = __builtin_amdgcn_readfirstlane(tid >> 6);
;     const long rowbase = (long)b * SEQ; const int q0 = qb * 256, qw0 = q0 + wid * 32;
;     const bf16_t* Qw = Q + (rowbase + qw0) * DM + hh * 64;
;     const bf16_t* Kh = K + rowbase * DM + hh * 64; const bf16_t* Vh = V + rowbase * DM + hh * 64;
;     const unsigned lds0 = (unsigned)(uintptr_t)shm;
;     const bf16_t* ksrc = Kh + (long)lane * DM + wid * 8;
;     const bf16_t* vsrc = Vh + (long)(16 * (wid & 3) + (lane >> 2)) * DM + (wid >> 2) * 32 + (lane & 3) * 8;
;     const bf16_t* fsrc = FS3 + ((long)(b * 8 + hh) * SEQ + lane) * 8;
;     const float* Frow = F2 + (long)(b * 8 + hh) * SEQ;
;     const unsigned kdst = lds0 + L_K + wid * 1024, vdst = lds0 + L_V + wid * 1024, fdst = lds0 + L_F;
;     ...
;     const int NT = 4 * qb + 4;
;     FOX_DMA(NT - 1, (NT - 1) & 3); FOX_DMA(NT - 2, (NT - 2) & 3);
; __global__ void __launch_bounds__(NWAVES * 64, 2) fwd_megakernel(Args args) {
;     ...
;             if (idx < 1024u) { const int qb = 31 - (int)(idx >> 5), bh = (int)(idx & 31);
;                 att::fox_unit(bh >> 3, bh & 7, qb, QB, KB, VB, OB, F2, FS3, CTL + 64, SS, lds); }
.LBB0_408:
	s_and_b64 vcc, exec, s[0:1]
	s_cbranch_vccz .LBB0_357
	v_mov_b32_e32 v175, 0
	v_mov_b32_e32 v176, 0
	s_lshr_b32 s3, s77, 5
	s_lshl_b32 s0, s77, 10
	s_sub_i32 s2, 31, s3
	v_readfirstlane_b32 s13, v178
	s_and_b32 s12, s0, 0x6000
	s_and_b32 s16, s77, 7
	s_lshr_b32 s15, s13, 6
	s_lshl_b32 s10, s2, 8
	s_lshl_b32 s5, s12, 11
	s_add_u32 s0, s88, s5
	s_addc_u32 s1, s95, 0
	s_lshl_b32 s6, s16, 7
	s_add_u32 s0, s0, s6
	s_addc_u32 s1, s1, 0
	s_add_u32 s5, s96, s5
	s_addc_u32 s7, s97, 0
	s_add_u32 s6, s5, s6
	s_addc_u32 s7, s7, 0
	v_lshl_add_u64 v[4:5], s[0:1], 0, v[148:149]
	s_lshr_b32 s0, s13, 2
	v_and_or_b32 v2, s0, 48, v135
	s_and_b32 s5, s77, 31
	s_lshl_b32 s80, s15, 4
	v_lshlrev_b32_e32 v2, 10, v2
	s_lshl_b32 s11, s5, 13
	v_lshl_add_u64 v[156:157], v[4:5], 0, s[80:81]
	v_lshl_add_u64 v[4:5], v[2:3], 1, s[6:7]
	s_and_b32 s80, s0, 0x3fffffc0
	v_or_b32_e32 v2, s11, v180
	v_readlane_b32 s0, v249, 25
	v_lshl_add_u64 v[4:5], v[4:5], 0, s[80:81]
	v_lshlrev_b32_e32 v2, 4, v2
	v_readlane_b32 s1, v249, 26
	s_lshl_b32 s6, s15, 10
	s_or_b32 s80, s10, 0xc0
	v_mov_b32_e32 v155, v3
	v_lshl_add_u64 v[160:161], s[0:1], 0, v[2:3]
	s_lshl_b64 s[0:1], s[80:81], 11
	s_add_i32 s93, s6, 0
	v_lshl_add_u64 v[158:159], v[4:5], 0, v[154:155]
	v_lshl_add_u64 v[4:5], v[156:157], 0, s[0:1]
	s_add_i32 s6, s93, 0x6000
	s_mov_b32 s7, m0
	s_mov_b32 m0, s6
	s_nop 0
	global_load_lds_dwordx4 v[4:5], off
	s_mov_b32 m0, s7
	v_lshl_add_u64 v[4:5], v[158:159], 0, s[0:1]
	s_add_i32 s0, s93, 0xe000
	s_mov_b32 s1, m0
	s_mov_b32 m0, s0
	s_nop 0
	global_load_lds_dwordx4 v[4:5], off
	s_mov_b32 m0, s1
	s_cmp_lt_u32 s13, 64
	s_cselect_b64 s[6:7], -1, 0
	s_cmp_gt_u32 s13, 63
	s_cbranch_scc1 .LBB0_411
	v_lshl_add_u64 v[4:5], s[80:81], 4, v[160:161]
	v_readlane_b32 s1, v249, 49
	s_mov_b32 s0, m0
	s_mov_b32 m0, s1
	s_nop 0
	global_load_lds_dwordx4 v[4:5], off
	s_mov_b32 m0, s0

; #define LAS3 __attribute__((address_space(3)))
; __device__ __forceinline__ unsigned cvtpk(float lo, float hi) { f32x2_t v = {lo, hi}; bf16x2_t b = __builtin_convertvector(v, bf16x2_t); return __builtin_bit_cast(unsigned, b); }
; __device__ __forceinline__ s16x4 vtr(const LAS3 unsigned char* p) { return __builtin_bit_cast(s16x4, __builtin_amdgcn_ds_read_tr16_b64_v4i16((LAS3 v4i16_t*)p)); }
; __device__ __forceinline__ void fox_unit(int b, int hh, int qb, const bf16_t* Q, const bf16_t* __restrict__ K, const bf16_t* __restrict__ V, bf16_t* O, ...
;     ...
;             for (int r = 0; r < 16; ++r) { p0[r] = __builtin_amdgcn_exp2f(p0[r]); p1[r] = __builtin_amdgcn_exp2f(p1[r]); }
;             u32x4 pw[4];
; #pragma unroll
;             for (int i = 0; i < 4; ++i) { pw[0][i] = cvtpk(p0[2 * i], p0[2 * i + 1]); pw[1][i] = cvtpk(p0[8 + 2 * i], p0[8 + 2 * i + 1]); pw[2][i] = cvtpk(p1[2 * i], p1[2 * i + 1]); pw[3][i] = cvtpk(p1[8 + 2 * i], p1[8 + 2 * i + 1]); }
;             const LAS3 unsigned char* vp = vp0 + slot * SLOTB;
; #pragma unroll
;             for (int ks = 0; ks < 4; ++ks) {
;                 const s16x4 l0 = vtr(vp + ks * 1024), h0 = vtr(vp + ks * 1024 + 512), l1 = vtr(vp + 4096 + ks * 1024), h1 = vtr(vp + 4096 + ks * 1024 + 512);
;                 const bf16x8 v0 = (bf16x8){l0[0], l0[1], l0[2], l0[3], h0[0], h0[1], h0[2], h0[3]}, v1 = (bf16x8){l1[0], l1[1], l1[2], l1[3], h1[0], h1[1], h1[2], h1[3]};
;                 const bf16x8 pf = __builtin_bit_cast(bf16x8, pw[ks]);
;                 o0 = __builtin_amdgcn_mfma_f32_32x32x16_bf16(v0, pf, o0, 0, 0, 0);
;                 o1 = __builtin_amdgcn_mfma_f32_32x32x16_bf16(v1, pf, o1, 0, 0, 0);
;                 lacc = __builtin_amdgcn_mfma_f32_32x32x16_bf16(onesA, pf, lacc, 0, 0, 0);
;             }
.LBB0_430:
	s_nop 7
	v_exp_f32_e32 v82, v82
	v_exp_f32_e32 v83, v83
	v_exp_f32_e32 v84, v84
	v_exp_f32_e32 v85, v85
	v_exp_f32_e32 v86, v86
	v_exp_f32_e32 v87, v87
	v_exp_f32_e32 v88, v88
	v_exp_f32_e32 v89, v89
	v_cvt_pk_bf16_f32 v228, v82, v83
	v_cvt_pk_bf16_f32 v229, v84, v85
	v_cvt_pk_bf16_f32 v230, v86, v87
	v_cvt_pk_bf16_f32 v231, v88, v89
	s_waitcnt lgkmcnt(0)
	s_nop 0
	v_mfma_f32_32x32x16_bf16 v[34:49], v[188:191], v[228:231], v[34:49]
	v_exp_f32_e32 v90, v90
	v_exp_f32_e32 v91, v91
	v_exp_f32_e32 v92, v92
	v_mfma_f32_32x32x16_bf16 v[18:33], v[192:195], v[228:231], v[18:33]
	v_exp_f32_e32 v93, v93
	v_exp_f32_e32 v94, v94
	v_exp_f32_e32 v95, v95
	v_exp_f32_e32 v96, v96
	v_exp_f32_e32 v97, v97
	v_add_f32_e32 v175, v175, v82
	v_add_f32_e32 v176, v176, v83
	v_add_f32_e32 v175, v175, v84
	v_add_f32_e32 v176, v176, v85
	v_cvt_pk_bf16_f32 v232, v90, v91
	v_cvt_pk_bf16_f32 v233, v92, v93
	v_cvt_pk_bf16_f32 v234, v94, v95
	v_cvt_pk_bf16_f32 v235, v96, v97
	v_add_f32_e32 v175, v175, v86
	v_add_f32_e32 v176, v176, v87
	v_mfma_f32_32x32x16_bf16 v[34:49], v[196:199], v[232:235], v[34:49]
	v_exp_f32_e32 v98, v98
	v_exp_f32_e32 v99, v99
	v_exp_f32_e32 v100, v100
	v_mfma_f32_32x32x16_bf16 v[18:33], v[200:203], v[232:235], v[18:33]
	v_exp_f32_e32 v101, v101
	v_exp_f32_e32 v102, v102
	v_exp_f32_e32 v103, v103
	v_exp_f32_e32 v104, v104
	v_exp_f32_e32 v105, v105
	v_add_f32_e32 v175, v175, v88
	v_add_f32_e32 v176, v176, v89
	v_add_f32_e32 v175, v175, v90
	v_add_f32_e32 v176, v176, v91
	v_cvt_pk_bf16_f32 v236, v98, v99
	v_cvt_pk_bf16_f32 v237, v100, v101
	v_cvt_pk_bf16_f32 v238, v102, v103
	v_cvt_pk_bf16_f32 v239, v104, v105
	v_add_f32_e32 v175, v175, v92
	v_add_f32_e32 v176, v176, v93
	v_mfma_f32_32x32x16_bf16 v[34:49], v[204:207], v[236:239], v[34:49]
	v_exp_f32_e32 v106, v106
	v_exp_f32_e32 v107, v107
	v_exp_f32_e32 v108, v108
	v_mfma_f32_32x32x16_bf16 v[18:33], v[208:211], v[236:239], v[18:33]
	v_exp_f32_e32 v109, v109
	v_exp_f32_e32 v110, v110
	v_exp_f32_e32 v111, v111
	v_exp_f32_e32 v112, v112
	v_exp_f32_e32 v113, v113
	v_add_f32_e32 v175, v175, v94
	v_add_f32_e32 v176, v176, v95
	v_add_f32_e32 v175, v175, v96
	v_add_f32_e32 v176, v176, v97
	v_cvt_pk_bf16_f32 v240, v106, v107
	v_cvt_pk_bf16_f32 v241, v108, v109
	v_cvt_pk_bf16_f32 v242, v110, v111
	v_cvt_pk_bf16_f32 v243, v112, v113
	v_add_f32_e32 v175, v175, v98
	v_add_f32_e32 v176, v176, v99
	v_mfma_f32_32x32x16_bf16 v[34:49], v[212:215], v[240:243], v[34:49]
	v_add_f32_e32 v175, v175, v100
	v_add_f32_e32 v176, v176, v101
	v_add_f32_e32 v175, v175, v102
	v_add_f32_e32 v176, v176, v103
	v_add_f32_e32 v175, v175, v104
	v_add_f32_e32 v176, v176, v105
	v_mfma_f32_32x32x16_bf16 v[18:33], v[216:219], v[240:243], v[18:33]
	v_add_f32_e32 v175, v175, v106
	v_add_f32_e32 v176, v176, v107
	v_add_f32_e32 v175, v175, v108
	v_add_f32_e32 v176, v176, v109
	v_add_f32_e32 v175, v175, v110
	v_add_f32_e32 v176, v176, v111
	v_add_f32_e32 v175, v175, v112
	v_add_f32_e32 v176, v176, v113

; __device__ __forceinline__ void fox_unit(int b, int hh, int qb, const bf16_t* Q, const bf16_t* __restrict__ K, const bf16_t* __restrict__ V, bf16_t* O, ...
;     ...
;     { const float inv = 1.0f / lacc[0];
; #pragma unroll
;         for (int r = 0; r < 16; ++r) { o0[r] *= inv; o1[r] *= inv; } }
;     float sq = 0.f;
; #pragma unroll
;     for (int r = 0; r < 16; ++r) sq += o0[r] * o0[r] + o1[r] * o1[r];
;     sq += other_half(sq);
;     if (hi == 0) SS[(size_t)(rowbase + qw0 + r32) * 16 + hh] = sq;
.LBB0_437:
	v_add_f32_e32 v66, v175, v176
	v_mov_b32_e32 v175, v66
	v_mov_b32_e32 v176, v66
	s_nop 1
	v_permlane32_swap_b32_e32 v175, v176
	v_add_f32_e32 v66, v175, v176
	s_nop 4
	v_div_scale_f32 v2, s[0:1], v66, v66, 1.0
	v_rcp_f32_e32 v4, v2
	v_div_scale_f32 v5, vcc, 1.0, v66, 1.0
	v_fma_f32 v6, -v2, v4, 1.0
	v_fmac_f32_e32 v4, v6, v4
	v_mul_f32_e32 v6, v5, v4
	v_fma_f32 v7, -v2, v6, v5
	v_fmac_f32_e32 v6, v7, v4
	v_fma_f32 v2, -v2, v6, v5
	v_div_fmas_f32 v2, v2, v4, v6
	v_div_fixup_f32 v2, v2, v66, 1.0
	v_pk_mul_f32 v[6:7], v[2:3], v[34:35] op_sel_hi:[0,1]
	v_pk_mul_f32 v[4:5], v[2:3], v[18:19] op_sel_hi:[0,1]
	v_pk_mul_f32 v[14:15], v[2:3], v[36:37] op_sel_hi:[0,1]
	v_pk_mul_f32 v[10:11], v[2:3], v[20:21] op_sel_hi:[0,1]
	v_pk_mul_f32 v[20:21], v[2:3], v[24:25] op_sel_hi:[0,1]
	v_pk_mul_f32 v[24:25], v[2:3], v[30:31] op_sel_hi:[0,1]
	v_pk_mul_f32 v[30:31], v[2:3], v[32:33] op_sel_hi:[0,1]
	v_pk_mul_f32 v[32:33], v[6:7], v[6:7]
	v_pk_mul_f32 v[12:13], v[2:3], v[38:39] op_sel_hi:[0,1]
	v_pk_fma_f32 v[32:33], v[4:5], v[4:5], v[32:33]
	v_pk_mul_f32 v[38:39], v[14:15], v[14:15]
	v_pk_mul_f32 v[8:9], v[2:3], v[22:23] op_sel_hi:[0,1]
	v_pk_mul_f32 v[22:23], v[2:3], v[40:41] op_sel_hi:[0,1]
	v_pk_mul_f32 v[18:19], v[2:3], v[42:43] op_sel_hi:[0,1]
	v_pk_mul_f32 v[16:17], v[2:3], v[26:27] op_sel_hi:[0,1]
	v_pk_mul_f32 v[34:35], v[2:3], v[44:45] op_sel_hi:[0,1]
	v_pk_mul_f32 v[26:27], v[2:3], v[28:29] op_sel_hi:[0,1]
	v_pk_mul_f32 v[28:29], v[2:3], v[46:47] op_sel_hi:[0,1]
	v_pk_mul_f32 v[36:37], v[2:3], v[48:49] op_sel_hi:[0,1]
	v_pk_fma_f32 v[38:39], v[10:11], v[10:11], v[38:39]
	v_add_f32_e32 v2, v32, v33
	v_pk_mul_f32 v[40:41], v[12:13], v[12:13]
	v_add_f32_e32 v2, v38, v2
	v_pk_fma_f32 v[40:41], v[8:9], v[8:9], v[40:41]
	v_add_f32_e32 v2, v39, v2
	v_pk_mul_f32 v[42:43], v[22:23], v[22:23]
	v_add_f32_e32 v2, v40, v2
	v_pk_fma_f32 v[42:43], v[20:21], v[20:21], v[42:43]
	v_add_f32_e32 v2, v41, v2
	v_pk_mul_f32 v[44:45], v[18:19], v[18:19]
	v_add_f32_e32 v2, v42, v2
	v_pk_fma_f32 v[44:45], v[16:17], v[16:17], v[44:45]
	v_add_f32_e32 v2, v43, v2
	v_pk_mul_f32 v[46:47], v[34:35], v[34:35]
	v_add_f32_e32 v2, v44, v2
	v_pk_fma_f32 v[46:47], v[26:27], v[26:27], v[46:47]
	v_add_f32_e32 v2, v45, v2
	v_pk_mul_f32 v[48:49], v[28:29], v[28:29]
	v_add_f32_e32 v2, v46, v2
	v_pk_fma_f32 v[48:49], v[24:25], v[24:25], v[48:49]
	v_add_f32_e32 v2, v47, v2
	v_pk_mul_f32 v[50:51], v[36:37], v[36:37]
	v_add_f32_e32 v2, v48, v2
	v_pk_fma_f32 v[50:51], v[30:31], v[30:31], v[50:51]
	v_add_f32_e32 v2, v49, v2
	v_add_f32_e32 v2, v50, v2
	v_add_f32_e32 v32, v51, v2
	v_mov_b32_e32 v33, v32
	v_mov_b32_e32 v38, v32
	s_nop 1
	v_permlane32_swap_b32_e32 v33, v38
	s_and_saveexec_b64 s[0:1], s[8:9]
	s_cbranch_execz .LBB0_356
	v_or_b32_e32 v2, s80, v182
	v_readlane_b32 s2, v249, 41
	v_lshlrev_b64 v[40:41], 6, v[2:3]
	v_readlane_b32 s3, v249, 42
	v_cmp_eq_u32_e32 vcc, v33, v32
	s_nop 0
	v_lshl_add_u64 v[40:41], s[2:3], 0, v[40:41]
	v_readlane_b32 s2, v249, 60
	s_lshl_b32 s80, s2, 2
	v_cndmask_b32_e32 v2, v33, v38, vcc
	v_lshl_add_u64 v[40:41], v[40:41], 0, s[80:81]
	v_add_f32_e32 v2, v32, v2
	global_store_dword v[40:41], v2, off
	s_branch .LBB0_356
